# diff tile loop code placement: rare blocks out of line, exit-flag computation in line, rescale decision branches on vccz (no arithmetic change)
# speedup vs baseline: 1.0325x; 1.0054x over previous
.LBB0_221:
	s_cmp_gt_u32 s27, s29
	s_cbranch_scc1 .LBB0_226
	v_add_f32_e32 v230, v128, v172
	v_add_f32_e32 v231, v174, v176
	v_add_f32_e32 v230, v177, v230
	v_add_f32_e32 v231, v180, v231
	s_waitcnt lgkmcnt(7)
	v_mfma_f32_32x32x16_bf16 v[82:97], v[66:69], v[98:101], 0
	v_add_f32_e32 v230, v181, v230
	v_add_f32_e32 v231, v183, v231
	v_add_f32_e32 v230, v184, v230
	v_add_f32_e32 v231, v185, v231
	s_waitcnt lgkmcnt(6)
	v_mfma_f32_32x32x16_bf16 v[66:81], v[70:73], v[98:101], 0
	v_add_f32_e32 v230, v186, v230
	v_add_f32_e32 v231, v188, v231
	v_add_f32_e32 v230, v187, v230
	v_add_f32_e32 v231, v189, v231
	s_add_i32 s28, s29, s79
	s_add_i32 s73, s81, s79
	s_add_u32 s2, s74, s48
	s_addc_u32 s3, s75, 0
	s_add_i32 s8, s46, 0x16000
	s_mov_b32 s9, m0
	s_mov_b32 m0, s8
	s_nop 0
	global_load_lds_dwordx4 v156, s[2:3]
	s_mov_b32 m0, s9
	s_add_i32 s3, s28, 5
	s_max_i32 s96, s3, 0
	s_add_i32 s2, s46, 0x8000
	s_lshl_b64 s[8:9], s[96:97], 19
	s_add_u32 s8, s89, s8
	s_addc_u32 s9, s90, s9
	s_mov_b32 s10, m0
	s_mov_b32 m0, s2
	s_nop 0
	global_load_lds_dwordx4 v154, s[8:9]
	s_mov_b32 m0, s10
	s_add_i32 s2, s46, 0xa000
	s_mov_b32 s10, m0
	s_mov_b32 m0, s2
	s_nop 0
	global_load_lds_dwordx4 v155, s[8:9]
	s_mov_b32 m0, s10
	s_waitcnt lgkmcnt(5)
	v_mfma_f32_32x32x16_bf16 v[82:97], v[210:213], v[102:105], v[82:97]
	v_add_f32_e32 v230, v190, v230
	v_add_f32_e32 v231, v191, v231
	v_add_f32_e32 v230, v121, v230
	v_add_f32_e32 v231, v122, v231
	s_waitcnt lgkmcnt(4)
	v_mfma_f32_32x32x16_bf16 v[66:81], v[214:217], v[102:105], v[66:81]
	v_add_f32_e32 v230, v123, v230
	v_add_f32_e32 v231, v124, v231
	v_add_f32_e32 v230, v125, v230
	v_add_f32_e32 v231, v126, v231
	s_waitcnt lgkmcnt(3)
	v_mfma_f32_32x32x16_bf16 v[82:97], v[218:221], v[106:109], v[82:97]
	v_add_f32_e32 v230, v127, v230
	v_add_f32_e32 v231, v129, v231
	v_add_f32_e32 v230, v142, v230
	v_add_f32_e32 v231, v175, v231
	s_waitcnt lgkmcnt(2)
	v_mfma_f32_32x32x16_bf16 v[66:81], v[222:225], v[106:109], v[66:81]
	v_add_f32_e32 v230, v173, v230
	v_add_f32_e32 v231, v178, v231
	v_add_f32_e32 v230, v179, v230
	v_add_f32_e32 v231, v182, v231
	s_waitcnt lgkmcnt(1)
	v_mfma_f32_32x32x16_bf16 v[82:97], v[226:229], v[110:113], v[82:97]
	v_add_f32_e32 v230, v192, v230
	v_add_f32_e32 v231, v193, v231
	v_add_f32_e32 v230, v230, v231
	v_add_f32_e32 v118, v118, v230
	s_waitcnt lgkmcnt(0)
	v_mfma_f32_32x32x16_bf16 v[66:81], v[234:237], v[110:113], v[66:81]
	s_add_i32 s2, s79, 3
	v_cvt_f32_i32_e32 v238, s2
	v_or_b32_sdwa v132, v238, v157 dst_sel:DWORD dst_unused:UNUSED_PAD src0_sel:WORD_1 src1_sel:DWORD
	v_or_b32_sdwa v133, v238, v157 dst_sel:DWORD dst_unused:UNUSED_PAD src0_sel:WORD_1 src1_sel:DWORD
	ds_read_b64_tr_b16 v[210:211], v146 offset:49152
	ds_read_b64_tr_b16 v[212:213], v147 offset:49152
	ds_read_b64_tr_b16 v[214:215], v148 offset:49152
	ds_read_b64_tr_b16 v[216:217], v149 offset:49152
	v_mfma_f32_32x32x16_bf16 v[82:97], v[132:135], v[114:117], v[82:97]
	v_or_b32_sdwa v132, v238, v158 dst_sel:DWORD dst_unused:UNUSED_PAD src0_sel:WORD_1 src1_sel:DWORD
	v_or_b32_sdwa v133, v238, v158 dst_sel:DWORD dst_unused:UNUSED_PAD src0_sel:WORD_1 src1_sel:DWORD
	ds_read_b64_tr_b16 v[218:219], v150 offset:49152
	ds_read_b64_tr_b16 v[220:221], v151 offset:49152
	ds_read_b64_tr_b16 v[222:223], v152 offset:49152
	ds_read_b64_tr_b16 v[224:225], v153 offset:49152
	v_mfma_f32_32x32x16_bf16 v[66:81], v[132:135], v[114:117], v[66:81]
	ds_read_b64_tr_b16 v[226:227], v146 offset:53248
	ds_read_b64_tr_b16 v[228:229], v147 offset:53248
	ds_read_b64_tr_b16 v[234:235], v148 offset:53248
	ds_read_b64_tr_b16 v[236:237], v149 offset:53248
	v_cvt_pk_bf16_f32 v194, v128, v174
	v_cvt_pk_bf16_f32 v195, v172, v176
	v_cvt_pk_bf16_f32 v196, v177, v180
	v_cvt_pk_bf16_f32 v197, v181, v183
	v_cvt_pk_bf16_f32 v198, v184, v185
	v_cvt_pk_bf16_f32 v199, v186, v188
	v_cvt_pk_bf16_f32 v200, v187, v189
	v_cvt_pk_bf16_f32 v201, v190, v191
	v_cvt_pk_bf16_f32 v202, v121, v122
	v_cvt_pk_bf16_f32 v203, v123, v124
	v_cvt_pk_bf16_f32 v204, v125, v126
	v_cvt_pk_bf16_f32 v205, v127, v129
	v_cvt_pk_bf16_f32 v206, v142, v175
	v_cvt_pk_bf16_f32 v207, v173, v178
	v_cvt_pk_bf16_f32 v208, v179, v182
	v_cvt_pk_bf16_f32 v209, v192, v193
	s_cmp_lg_u32 s73, -7
	s_cselect_b64 s[8:9], -1, 0
	s_cmp_eq_u32 s73, -7
	s_cselect_b64 s[12:13], -1, 0
	s_and_b64 vcc, exec, s[8:9]
	s_cbranch_vccz .Ldf_mask_0
.LBB0_224:
	s_andn2_b64 vcc, exec, s[12:13]
	v_max_f32_e32 v132, v82, v66
	v_max_f32_e32 v133, v83, v67
	v_max3_f32 v132, v132, v84, v68
	v_max3_f32 v133, v133, v85, v69
	v_max3_f32 v132, v132, v86, v70
	v_max3_f32 v133, v133, v87, v71
	v_max3_f32 v132, v132, v88, v72
	v_max3_f32 v133, v133, v89, v73
	v_max3_f32 v132, v132, v90, v74
	v_max3_f32 v133, v133, v91, v75
	v_max3_f32 v132, v132, v92, v76
	v_max3_f32 v133, v133, v93, v77
	v_max3_f32 v132, v132, v94, v78
	v_max3_f32 v133, v133, v95, v79
	v_max3_f32 v132, v132, v96, v80
	v_max3_f32 v133, v133, v97, v81
	v_max_f32_e32 v132, v132, v133
	v_mov_b32_e32 v133, v132
	s_nop 1
	v_permlane32_swap_b32_e32 v132, v133
	v_max_f32_e32 v132, v132, v133
	s_cbranch_vccz .Ldf_first_0
	v_cmp_lt_f32_e32 vcc, s84, v132
	s_mov_b64 s[12:13], 0
	s_cbranch_vccnz .Ldf_resc_0
.LBB0_231:
	s_waitcnt lgkmcnt(10)
	v_mfma_f32_32x32x16_bf16 v[2:17], v[210:213], v[194:197], v[2:17]
	ds_read_b64_tr_b16 v[210:211], v150 offset:53248
	ds_read_b64_tr_b16 v[212:213], v151 offset:53248
	v_exp_f32_e32 v121, v66
	v_exp_f32_e32 v122, v67
	s_waitcnt lgkmcnt(10)
	v_mfma_f32_32x32x16_bf16 v[18:33], v[214:217], v[194:197], v[18:33]
	ds_read_b64_tr_b16 v[214:215], v152 offset:53248
	ds_read_b64_tr_b16 v[216:217], v153 offset:53248
	v_exp_f32_e32 v123, v68
	v_exp_f32_e32 v124, v69
	s_waitcnt lgkmcnt(10)
	v_mfma_f32_32x32x16_bf16 v[34:49], v[218:221], v[194:197], v[34:49]
	ds_read_b64_tr_b16 v[218:219], v146 offset:57344
	ds_read_b64_tr_b16 v[220:221], v147 offset:57344
	v_exp_f32_e32 v125, v70
	v_exp_f32_e32 v126, v71
	s_waitcnt lgkmcnt(10)
	v_mfma_f32_32x32x16_bf16 v[50:65], v[222:225], v[194:197], v[50:65]
	ds_read_b64_tr_b16 v[222:223], v148 offset:57344
	ds_read_b64_tr_b16 v[224:225], v149 offset:57344
	v_exp_f32_e32 v127, v72
	v_exp_f32_e32 v129, v73
	v_mov_b32_e32 v238, 0x18020
	ds_read_b128 v[66:69], v238
	v_mov_b32_e32 v239, 0x18030
	ds_read_b128 v[70:73], v239
	s_waitcnt lgkmcnt(12)
	v_mfma_f32_32x32x16_bf16 v[2:17], v[226:229], v[198:201], v[2:17]
	ds_read_b64_tr_b16 v[226:227], v150 offset:57344
	ds_read_b64_tr_b16 v[228:229], v151 offset:57344
	v_exp_f32_e32 v128, v82
	v_exp_f32_e32 v174, v83
	s_waitcnt lgkmcnt(12)
	v_mfma_f32_32x32x16_bf16 v[18:33], v[234:237], v[198:201], v[18:33]
	ds_read_b64_tr_b16 v[234:235], v152 offset:57344
	ds_read_b64_tr_b16 v[236:237], v153 offset:57344
	v_exp_f32_e32 v172, v84
	v_exp_f32_e32 v176, v85
	s_waitcnt lgkmcnt(12)
	v_mfma_f32_32x32x16_bf16 v[34:49], v[210:213], v[198:201], v[34:49]
	ds_read_b64_tr_b16 v[210:211], v146 offset:61440
	ds_read_b64_tr_b16 v[212:213], v147 offset:61440
	v_exp_f32_e32 v177, v86
	v_exp_f32_e32 v180, v87
	s_waitcnt lgkmcnt(12)
	v_mfma_f32_32x32x16_bf16 v[50:65], v[214:217], v[198:201], v[50:65]
	ds_read_b64_tr_b16 v[214:215], v148 offset:61440
	ds_read_b64_tr_b16 v[216:217], v149 offset:61440
	v_exp_f32_e32 v181, v88
	v_exp_f32_e32 v183, v89
	s_waitcnt lgkmcnt(12)
	v_mfma_f32_32x32x16_bf16 v[2:17], v[218:221], v[202:205], v[2:17]
	ds_read_b64_tr_b16 v[218:219], v150 offset:61440
	ds_read_b64_tr_b16 v[220:221], v151 offset:61440
	v_exp_f32_e32 v184, v90
	v_exp_f32_e32 v185, v91
	s_waitcnt lgkmcnt(12)
	v_mfma_f32_32x32x16_bf16 v[18:33], v[222:225], v[202:205], v[18:33]
	ds_read_b64_tr_b16 v[222:223], v152 offset:61440
	ds_read_b64_tr_b16 v[224:225], v153 offset:61440
	v_exp_f32_e32 v186, v92
	v_exp_f32_e32 v188, v93
	s_waitcnt lgkmcnt(10)
	v_mfma_f32_32x32x16_bf16 v[34:49], v[226:229], v[202:205], v[34:49]
	v_exp_f32_e32 v187, v94
	v_exp_f32_e32 v189, v95
	s_waitcnt lgkmcnt(8)
	v_mfma_f32_32x32x16_bf16 v[50:65], v[234:237], v[202:205], v[50:65]
	v_exp_f32_e32 v190, v96
	v_exp_f32_e32 v191, v97
	s_waitcnt lgkmcnt(6)
	v_mfma_f32_32x32x16_bf16 v[2:17], v[210:213], v[206:209], v[2:17]
	v_exp_f32_e32 v142, v74
	v_exp_f32_e32 v175, v75
	v_and_b32_e32 v66, v66, v67
	v_and_b32_e32 v68, v68, v69
	s_waitcnt lgkmcnt(4)
	v_mfma_f32_32x32x16_bf16 v[18:33], v[214:217], v[206:209], v[18:33]
	v_exp_f32_e32 v173, v76
	v_exp_f32_e32 v178, v77
	v_and_b32_e32 v70, v70, v71
	v_and_b32_e32 v72, v72, v73
	s_waitcnt lgkmcnt(2)
	v_mfma_f32_32x32x16_bf16 v[34:49], v[218:221], v[206:209], v[34:49]
	v_exp_f32_e32 v179, v78
	v_exp_f32_e32 v182, v79
	v_and_b32_e32 v66, v66, v68
	v_and_b32_e32 v70, v70, v72
	s_waitcnt lgkmcnt(0)
	v_mfma_f32_32x32x16_bf16 v[50:65], v[222:225], v[206:209], v[50:65]
	v_exp_f32_e32 v192, v80
	v_exp_f32_e32 v193, v81
	v_and_b32_e32 v66, v66, v70
	s_andn2_b64 vcc, exec, s[12:13]
	s_cbranch_vccz .LBB0_240
	s_add_i32 s2, s28, 7
	s_cmp_gt_i32 s2, s82
	v_mov_b32_e32 v238, 0
	s_cbranch_scc1 .LBB0_233
.LBB0_241:
	s_add_i32 s2, s99, 0x80
	v_cvt_f32_i32_e32 v238, s2
	v_fma_f32 v238, v145, v238, v119
	v_sub_f32_e32 v238, v238, v120
	v_cmp_gt_f32_e32 vcc, s85, v238
	s_cmp_eq_u64 vcc, exec
	s_cselect_b64 s[8:9], -1, 0
	v_cndmask_b32_e64 v238, 0, 1, s[8:9]
.LBB0_233:
	s_and_saveexec_b64 s[8:9], s[6:7]

.LBB0_235:
	s_or_b64 exec, exec, s[8:9]
	s_add_i32 s2, 0, 0x18000
	s_waitcnt vmcnt(6) lgkmcnt(0)
	s_barrier
	v_cmp_ne_u32_e32 vcc, 0, v66
	ds_read_b128 v[66:69], v168 offset:8192
	ds_read_b128 v[70:73], v168 offset:12288
	ds_read_b128 v[210:213], v169 offset:8192
	ds_read_b128 v[214:217], v169 offset:12288
	ds_read_b128 v[218:221], v170 offset:8192
	ds_read_b128 v[222:225], v170 offset:12288
	ds_read_b128 v[226:229], v171 offset:8192
	ds_read_b128 v[234:237], v171 offset:12288
	s_mov_b64 s[8:9], -1
	s_mov_b32 s10, 0
	s_cbranch_vccnz .LBB0_268
	v_add_f32_e32 v230, v128, v172
	v_add_f32_e32 v231, v174, v176
	v_add_f32_e32 v230, v177, v230
	v_add_f32_e32 v231, v180, v231
	s_waitcnt lgkmcnt(7)
	v_mfma_f32_32x32x16_bf16 v[82:97], v[66:69], v[98:101], 0
	v_add_f32_e32 v230, v181, v230
	v_add_f32_e32 v231, v183, v231
	v_add_f32_e32 v230, v184, v230
	v_add_f32_e32 v231, v185, v231
	s_waitcnt lgkmcnt(6)
	v_mfma_f32_32x32x16_bf16 v[66:81], v[70:73], v[98:101], 0
	v_add_f32_e32 v230, v186, v230
	v_add_f32_e32 v231, v188, v231
	v_add_f32_e32 v230, v187, v230
	v_add_f32_e32 v231, v189, v231
	s_add_i32 s8, s28, 3
	s_max_i32 s96, s8, 0
	s_lshl_b64 s[8:9], s[96:97], 19
	s_add_u32 s10, s74, s8
	s_addc_u32 s11, s75, s9
	s_mov_b32 s12, m0
	s_mov_b32 m0, s47
	s_nop 0
	global_load_lds_dwordx4 v156, s[10:11]
	s_mov_b32 m0, s12
	s_add_u32 s10, s89, s48
	s_addc_u32 s11, s90, 0
	s_mov_b32 s12, m0
	s_mov_b32 m0, s54
	s_nop 0
	global_load_lds_dwordx4 v154, s[10:11]
	s_mov_b32 m0, s12
	s_nop 0
	s_mov_b32 s12, m0
	s_mov_b32 m0, s78
	s_nop 0
	global_load_lds_dwordx4 v155, s[10:11]
	s_mov_b32 m0, s12
	s_waitcnt lgkmcnt(5)
	v_mfma_f32_32x32x16_bf16 v[82:97], v[210:213], v[102:105], v[82:97]
	v_add_f32_e32 v230, v190, v230
	v_add_f32_e32 v231, v191, v231
	v_add_f32_e32 v230, v121, v230
	v_add_f32_e32 v231, v122, v231
	s_waitcnt lgkmcnt(4)
	v_mfma_f32_32x32x16_bf16 v[66:81], v[214:217], v[102:105], v[66:81]
	v_add_f32_e32 v230, v123, v230
	v_add_f32_e32 v231, v124, v231
	v_add_f32_e32 v230, v125, v230
	v_add_f32_e32 v231, v126, v231
	s_waitcnt lgkmcnt(3)
	v_mfma_f32_32x32x16_bf16 v[82:97], v[218:221], v[106:109], v[82:97]
	v_add_f32_e32 v230, v127, v230
	v_add_f32_e32 v231, v129, v231
	v_add_f32_e32 v230, v142, v230
	v_add_f32_e32 v231, v175, v231
	s_waitcnt lgkmcnt(2)
	v_mfma_f32_32x32x16_bf16 v[66:81], v[222:225], v[106:109], v[66:81]
	v_add_f32_e32 v230, v173, v230
	v_add_f32_e32 v231, v178, v231
	v_add_f32_e32 v230, v179, v230
	v_add_f32_e32 v231, v182, v231
	s_waitcnt lgkmcnt(1)
	v_mfma_f32_32x32x16_bf16 v[82:97], v[226:229], v[110:113], v[82:97]
	v_add_f32_e32 v230, v192, v230
	v_add_f32_e32 v231, v193, v231
	v_add_f32_e32 v230, v230, v231
	v_add_f32_e32 v118, v118, v230
	s_waitcnt lgkmcnt(0)
	v_mfma_f32_32x32x16_bf16 v[66:81], v[234:237], v[110:113], v[66:81]
	s_add_i32 s10, s79, 2
	v_cvt_f32_i32_e32 v238, s10
	v_or_b32_sdwa v132, v238, v157 dst_sel:DWORD dst_unused:UNUSED_PAD src0_sel:WORD_1 src1_sel:DWORD
	v_or_b32_sdwa v133, v238, v157 dst_sel:DWORD dst_unused:UNUSED_PAD src0_sel:WORD_1 src1_sel:DWORD
	ds_read_b64_tr_b16 v[210:211], v146
	ds_read_b64_tr_b16 v[212:213], v147
	ds_read_b64_tr_b16 v[214:215], v148
	ds_read_b64_tr_b16 v[216:217], v149
	v_mfma_f32_32x32x16_bf16 v[82:97], v[132:135], v[114:117], v[82:97]
	v_or_b32_sdwa v132, v238, v158 dst_sel:DWORD dst_unused:UNUSED_PAD src0_sel:WORD_1 src1_sel:DWORD
	v_or_b32_sdwa v133, v238, v158 dst_sel:DWORD dst_unused:UNUSED_PAD src0_sel:WORD_1 src1_sel:DWORD
	ds_read_b64_tr_b16 v[218:219], v150
	ds_read_b64_tr_b16 v[220:221], v151
	ds_read_b64_tr_b16 v[222:223], v152
	ds_read_b64_tr_b16 v[224:225], v153
	v_mfma_f32_32x32x16_bf16 v[66:81], v[132:135], v[114:117], v[66:81]
	ds_read_b64_tr_b16 v[226:227], v146 offset:4096
	ds_read_b64_tr_b16 v[228:229], v147 offset:4096
	ds_read_b64_tr_b16 v[234:235], v148 offset:4096
	ds_read_b64_tr_b16 v[236:237], v149 offset:4096
	v_cvt_pk_bf16_f32 v194, v128, v174
	v_cvt_pk_bf16_f32 v195, v172, v176
	v_cvt_pk_bf16_f32 v196, v177, v180
	v_cvt_pk_bf16_f32 v197, v181, v183
	v_cvt_pk_bf16_f32 v198, v184, v185
	v_cvt_pk_bf16_f32 v199, v186, v188
	v_cvt_pk_bf16_f32 v200, v187, v189
	v_cvt_pk_bf16_f32 v201, v190, v191
	v_cvt_pk_bf16_f32 v202, v121, v122
	v_cvt_pk_bf16_f32 v203, v123, v124
	v_cvt_pk_bf16_f32 v204, v125, v126
	v_cvt_pk_bf16_f32 v205, v127, v129
	v_cvt_pk_bf16_f32 v206, v142, v175
	v_cvt_pk_bf16_f32 v207, v173, v178
	v_cvt_pk_bf16_f32 v208, v179, v182
	v_cvt_pk_bf16_f32 v209, v192, v193
	s_cmp_lg_u32 s73, -6
	s_cselect_b64 s[12:13], -1, 0
	s_cmp_eq_u32 s73, -6
	s_cselect_b64 s[14:15], -1, 0
	s_and_b64 vcc, exec, s[12:13]
	s_cbranch_vccz .Ldf_mask_1
.LBB0_238:
	s_andn2_b64 vcc, exec, s[14:15]
	v_max_f32_e32 v132, v82, v66
	v_max_f32_e32 v133, v83, v67
	v_max3_f32 v132, v132, v84, v68
	v_max3_f32 v133, v133, v85, v69
	v_max3_f32 v132, v132, v86, v70
	v_max3_f32 v133, v133, v87, v71
	v_max3_f32 v132, v132, v88, v72
	v_max3_f32 v133, v133, v89, v73
	v_max3_f32 v132, v132, v90, v74
	v_max3_f32 v133, v133, v91, v75
	v_max3_f32 v132, v132, v92, v76
	v_max3_f32 v133, v133, v93, v77
	v_max3_f32 v132, v132, v94, v78
	v_max3_f32 v133, v133, v95, v79
	v_max3_f32 v132, v132, v96, v80
	v_max3_f32 v133, v133, v97, v81
	v_max_f32_e32 v132, v132, v133
	v_mov_b32_e32 v133, v132
	s_nop 1
	v_permlane32_swap_b32_e32 v132, v133
	v_max_f32_e32 v132, v132, v133
	s_cbranch_vccz .Ldf_first_1
	v_cmp_lt_f32_e32 vcc, s84, v132
	s_mov_b64 s[14:15], 0
	s_cbranch_vccnz .Ldf_resc_1
.LBB0_246:
	s_waitcnt lgkmcnt(10)
	v_mfma_f32_32x32x16_bf16 v[2:17], v[210:213], v[194:197], v[2:17]
	ds_read_b64_tr_b16 v[210:211], v150 offset:4096
	ds_read_b64_tr_b16 v[212:213], v151 offset:4096
	v_exp_f32_e32 v121, v66
	v_exp_f32_e32 v122, v67
	s_waitcnt lgkmcnt(10)
	v_mfma_f32_32x32x16_bf16 v[18:33], v[214:217], v[194:197], v[18:33]
	ds_read_b64_tr_b16 v[214:215], v152 offset:4096
	ds_read_b64_tr_b16 v[216:217], v153 offset:4096
	v_exp_f32_e32 v123, v68
	v_exp_f32_e32 v124, v69
	s_waitcnt lgkmcnt(10)
	v_mfma_f32_32x32x16_bf16 v[34:49], v[218:221], v[194:197], v[34:49]
	ds_read_b64_tr_b16 v[218:219], v146 offset:8192
	ds_read_b64_tr_b16 v[220:221], v147 offset:8192
	v_exp_f32_e32 v125, v70
	v_exp_f32_e32 v126, v71
	s_waitcnt lgkmcnt(10)
	v_mfma_f32_32x32x16_bf16 v[50:65], v[222:225], v[194:197], v[50:65]
	ds_read_b64_tr_b16 v[222:223], v148 offset:8192
	ds_read_b64_tr_b16 v[224:225], v149 offset:8192
	v_exp_f32_e32 v127, v72
	v_exp_f32_e32 v129, v73
	v_mov_b32_e32 v238, 0x18000
	ds_read_b128 v[66:69], v238
	v_mov_b32_e32 v239, 0x18010
	ds_read_b128 v[70:73], v239
	s_waitcnt lgkmcnt(12)
	v_mfma_f32_32x32x16_bf16 v[2:17], v[226:229], v[198:201], v[2:17]
	ds_read_b64_tr_b16 v[226:227], v150 offset:8192
	ds_read_b64_tr_b16 v[228:229], v151 offset:8192
	v_exp_f32_e32 v128, v82
	v_exp_f32_e32 v174, v83
	s_waitcnt lgkmcnt(12)
	v_mfma_f32_32x32x16_bf16 v[18:33], v[234:237], v[198:201], v[18:33]
	ds_read_b64_tr_b16 v[234:235], v152 offset:8192
	ds_read_b64_tr_b16 v[236:237], v153 offset:8192
	v_exp_f32_e32 v172, v84
	v_exp_f32_e32 v176, v85
	s_waitcnt lgkmcnt(12)
	v_mfma_f32_32x32x16_bf16 v[34:49], v[210:213], v[198:201], v[34:49]
	ds_read_b64_tr_b16 v[210:211], v146 offset:12288
	ds_read_b64_tr_b16 v[212:213], v147 offset:12288
	v_exp_f32_e32 v177, v86
	v_exp_f32_e32 v180, v87
	s_waitcnt lgkmcnt(12)
	v_mfma_f32_32x32x16_bf16 v[50:65], v[214:217], v[198:201], v[50:65]
	ds_read_b64_tr_b16 v[214:215], v148 offset:12288
	ds_read_b64_tr_b16 v[216:217], v149 offset:12288
	v_exp_f32_e32 v181, v88
	v_exp_f32_e32 v183, v89
	s_waitcnt lgkmcnt(12)
	v_mfma_f32_32x32x16_bf16 v[2:17], v[218:221], v[202:205], v[2:17]
	ds_read_b64_tr_b16 v[218:219], v150 offset:12288
	ds_read_b64_tr_b16 v[220:221], v151 offset:12288
	v_exp_f32_e32 v184, v90
	v_exp_f32_e32 v185, v91
	s_waitcnt lgkmcnt(12)
	v_mfma_f32_32x32x16_bf16 v[18:33], v[222:225], v[202:205], v[18:33]
	ds_read_b64_tr_b16 v[222:223], v152 offset:12288
	ds_read_b64_tr_b16 v[224:225], v153 offset:12288
	v_exp_f32_e32 v186, v92
	v_exp_f32_e32 v188, v93
	s_waitcnt lgkmcnt(10)
	v_mfma_f32_32x32x16_bf16 v[34:49], v[226:229], v[202:205], v[34:49]
	v_exp_f32_e32 v187, v94
	v_exp_f32_e32 v189, v95
	s_waitcnt lgkmcnt(8)
	v_mfma_f32_32x32x16_bf16 v[50:65], v[234:237], v[202:205], v[50:65]
	v_exp_f32_e32 v190, v96
	v_exp_f32_e32 v191, v97
	s_waitcnt lgkmcnt(6)
	v_mfma_f32_32x32x16_bf16 v[2:17], v[210:213], v[206:209], v[2:17]
	v_exp_f32_e32 v142, v74
	v_exp_f32_e32 v175, v75
	v_and_b32_e32 v66, v66, v67
	v_and_b32_e32 v68, v68, v69
	s_waitcnt lgkmcnt(4)
	v_mfma_f32_32x32x16_bf16 v[18:33], v[214:217], v[206:209], v[18:33]
	v_exp_f32_e32 v173, v76
	v_exp_f32_e32 v178, v77
	v_and_b32_e32 v70, v70, v71
	v_and_b32_e32 v72, v72, v73
	s_waitcnt lgkmcnt(2)
	v_mfma_f32_32x32x16_bf16 v[34:49], v[218:221], v[206:209], v[34:49]
	v_exp_f32_e32 v179, v78
	v_exp_f32_e32 v182, v79
	v_and_b32_e32 v66, v66, v68
	v_and_b32_e32 v70, v70, v72
	s_waitcnt lgkmcnt(0)
	v_mfma_f32_32x32x16_bf16 v[50:65], v[222:225], v[206:209], v[50:65]
	v_exp_f32_e32 v192, v80
	v_exp_f32_e32 v193, v81
	v_and_b32_e32 v66, v66, v70
	s_andn2_b64 vcc, exec, s[14:15]
	s_cbranch_vccz .LBB0_252
	s_add_i32 s10, s28, 6
	s_cmp_gt_i32 s10, s82
	v_mov_b32_e32 v238, 0
	s_cbranch_scc1 .LBB0_248
.LBB0_253:
	s_add_i32 s10, s99, 0x40
	v_cvt_f32_i32_e32 v238, s10
	v_fma_f32 v238, v145, v238, v119
	v_sub_f32_e32 v238, v238, v120
	v_cmp_gt_f32_e32 vcc, s85, v238
	s_cmp_eq_u64 vcc, exec
	s_cselect_b64 s[10:11], -1, 0
	v_cndmask_b32_e64 v238, 0, 1, s[10:11]
.LBB0_248:
	s_and_saveexec_b64 s[10:11], s[6:7]

.LBB0_252:
	s_nop 3
	v_pk_mul_f32 v[16:17], v[0:1], v[16:17] op_sel_hi:[0,1]
	v_pk_mul_f32 v[14:15], v[0:1], v[14:15] op_sel_hi:[0,1]
	v_pk_mul_f32 v[12:13], v[0:1], v[12:13] op_sel_hi:[0,1]
	v_pk_mul_f32 v[10:11], v[0:1], v[10:11] op_sel_hi:[0,1]
	v_pk_mul_f32 v[8:9], v[0:1], v[8:9] op_sel_hi:[0,1]
	v_pk_mul_f32 v[6:7], v[0:1], v[6:7] op_sel_hi:[0,1]
	v_pk_mul_f32 v[4:5], v[0:1], v[4:5] op_sel_hi:[0,1]
	v_pk_mul_f32 v[2:3], v[0:1], v[2:3] op_sel_hi:[0,1]
	v_pk_mul_f32 v[32:33], v[0:1], v[32:33] op_sel_hi:[0,1]
	v_pk_mul_f32 v[30:31], v[0:1], v[30:31] op_sel_hi:[0,1]
	v_pk_mul_f32 v[28:29], v[0:1], v[28:29] op_sel_hi:[0,1]
	v_pk_mul_f32 v[26:27], v[0:1], v[26:27] op_sel_hi:[0,1]
	v_pk_mul_f32 v[24:25], v[0:1], v[24:25] op_sel_hi:[0,1]
	v_pk_mul_f32 v[22:23], v[0:1], v[22:23] op_sel_hi:[0,1]
	v_pk_mul_f32 v[20:21], v[0:1], v[20:21] op_sel_hi:[0,1]
	v_pk_mul_f32 v[18:19], v[0:1], v[18:19] op_sel_hi:[0,1]
	v_pk_mul_f32 v[48:49], v[0:1], v[48:49] op_sel_hi:[0,1]
	v_pk_mul_f32 v[46:47], v[0:1], v[46:47] op_sel_hi:[0,1]
	v_pk_mul_f32 v[44:45], v[0:1], v[44:45] op_sel_hi:[0,1]
	v_pk_mul_f32 v[42:43], v[0:1], v[42:43] op_sel_hi:[0,1]
	v_pk_mul_f32 v[40:41], v[0:1], v[40:41] op_sel_hi:[0,1]
	v_pk_mul_f32 v[38:39], v[0:1], v[38:39] op_sel_hi:[0,1]
	v_pk_mul_f32 v[36:37], v[0:1], v[36:37] op_sel_hi:[0,1]
	v_pk_mul_f32 v[34:35], v[0:1], v[34:35] op_sel_hi:[0,1]
	v_pk_mul_f32 v[64:65], v[0:1], v[64:65] op_sel_hi:[0,1]
	v_pk_mul_f32 v[62:63], v[0:1], v[62:63] op_sel_hi:[0,1]
	v_pk_mul_f32 v[60:61], v[0:1], v[60:61] op_sel_hi:[0,1]
	v_pk_mul_f32 v[58:59], v[0:1], v[58:59] op_sel_hi:[0,1]
	v_pk_mul_f32 v[56:57], v[0:1], v[56:57] op_sel_hi:[0,1]
	v_pk_mul_f32 v[54:55], v[0:1], v[54:55] op_sel_hi:[0,1]
	v_pk_mul_f32 v[52:53], v[0:1], v[52:53] op_sel_hi:[0,1]
	v_pk_mul_f32 v[50:51], v[0:1], v[50:51] op_sel_hi:[0,1]
	s_add_i32 s10, s28, 6
	s_cmp_gt_i32 s10, s82
	v_mov_b32_e32 v238, 0
	s_cbranch_scc1 .LBB0_248
	s_branch .LBB0_253
.LBB0_254:
	v_add_f32_e32 v230, v128, v172
	v_add_f32_e32 v231, v174, v176
	v_add_f32_e32 v230, v177, v230
	v_add_f32_e32 v231, v180, v231
	s_waitcnt lgkmcnt(7)
	v_mfma_f32_32x32x16_bf16 v[82:97], v[66:69], v[98:101], 0
	v_add_f32_e32 v230, v181, v230
	v_add_f32_e32 v231, v183, v231
	v_add_f32_e32 v230, v184, v230
	v_add_f32_e32 v231, v185, v231
	s_waitcnt lgkmcnt(6)
	v_mfma_f32_32x32x16_bf16 v[66:81], v[70:73], v[98:101], 0
	v_add_f32_e32 v230, v186, v230
	v_add_f32_e32 v231, v188, v231
	v_add_f32_e32 v230, v187, v230
	v_add_f32_e32 v231, v189, v231
	s_add_i32 s10, s28, 2
	s_max_i32 s96, s10, 0
	s_lshl_b64 s[12:13], s[96:97], 19
	s_add_u32 s10, s74, s12
	s_addc_u32 s11, s75, s13
	s_mov_b32 s14, m0
	s_mov_b32 m0, s51
	s_nop 0
	global_load_lds_dwordx4 v156, s[10:11]
	s_mov_b32 m0, s14
	s_add_u32 s8, s89, s8
	s_addc_u32 s9, s90, s9
	s_mov_b32 s10, m0
	s_mov_b32 m0, s46
	s_nop 0
	global_load_lds_dwordx4 v154, s[8:9]
	s_mov_b32 m0, s10
	s_nop 0
	s_mov_b32 s10, m0
	s_mov_b32 m0, s76
	s_nop 0
	global_load_lds_dwordx4 v155, s[8:9]
	s_mov_b32 m0, s10
	s_waitcnt lgkmcnt(5)
	v_mfma_f32_32x32x16_bf16 v[82:97], v[210:213], v[102:105], v[82:97]
	v_add_f32_e32 v230, v190, v230
	v_add_f32_e32 v231, v191, v231
	v_add_f32_e32 v230, v121, v230
	v_add_f32_e32 v231, v122, v231
	s_waitcnt lgkmcnt(4)
	v_mfma_f32_32x32x16_bf16 v[66:81], v[214:217], v[102:105], v[66:81]
	v_add_f32_e32 v230, v123, v230
	v_add_f32_e32 v231, v124, v231
	v_add_f32_e32 v230, v125, v230
	v_add_f32_e32 v231, v126, v231
	s_waitcnt lgkmcnt(3)
	v_mfma_f32_32x32x16_bf16 v[82:97], v[218:221], v[106:109], v[82:97]
	v_add_f32_e32 v230, v127, v230
	v_add_f32_e32 v231, v129, v231
	v_add_f32_e32 v230, v142, v230
	v_add_f32_e32 v231, v175, v231
	s_waitcnt lgkmcnt(2)
	v_mfma_f32_32x32x16_bf16 v[66:81], v[222:225], v[106:109], v[66:81]
	v_add_f32_e32 v230, v173, v230
	v_add_f32_e32 v231, v178, v231
	v_add_f32_e32 v230, v179, v230
	v_add_f32_e32 v231, v182, v231
	s_waitcnt lgkmcnt(1)
	v_mfma_f32_32x32x16_bf16 v[82:97], v[226:229], v[110:113], v[82:97]
	v_add_f32_e32 v230, v192, v230
	v_add_f32_e32 v231, v193, v231
	v_add_f32_e32 v230, v230, v231
	v_add_f32_e32 v118, v118, v230
	s_waitcnt lgkmcnt(0)
	v_mfma_f32_32x32x16_bf16 v[66:81], v[234:237], v[110:113], v[66:81]
	s_add_i32 s8, s79, 1
	v_cvt_f32_i32_e32 v238, s8
	v_or_b32_sdwa v132, v238, v157 dst_sel:DWORD dst_unused:UNUSED_PAD src0_sel:WORD_1 src1_sel:DWORD
	v_or_b32_sdwa v133, v238, v157 dst_sel:DWORD dst_unused:UNUSED_PAD src0_sel:WORD_1 src1_sel:DWORD
	ds_read_b64_tr_b16 v[210:211], v146 offset:16384
	ds_read_b64_tr_b16 v[212:213], v147 offset:16384
	ds_read_b64_tr_b16 v[214:215], v148 offset:16384
	ds_read_b64_tr_b16 v[216:217], v149 offset:16384
	v_mfma_f32_32x32x16_bf16 v[82:97], v[132:135], v[114:117], v[82:97]
	v_or_b32_sdwa v132, v238, v158 dst_sel:DWORD dst_unused:UNUSED_PAD src0_sel:WORD_1 src1_sel:DWORD
	v_or_b32_sdwa v133, v238, v158 dst_sel:DWORD dst_unused:UNUSED_PAD src0_sel:WORD_1 src1_sel:DWORD
	ds_read_b64_tr_b16 v[218:219], v150 offset:16384
	ds_read_b64_tr_b16 v[220:221], v151 offset:16384
	ds_read_b64_tr_b16 v[222:223], v152 offset:16384
	ds_read_b64_tr_b16 v[224:225], v153 offset:16384
	v_mfma_f32_32x32x16_bf16 v[66:81], v[132:135], v[114:117], v[66:81]
	ds_read_b64_tr_b16 v[226:227], v146 offset:20480
	ds_read_b64_tr_b16 v[228:229], v147 offset:20480
	ds_read_b64_tr_b16 v[234:235], v148 offset:20480
	ds_read_b64_tr_b16 v[236:237], v149 offset:20480
	v_cvt_pk_bf16_f32 v194, v128, v174
	v_cvt_pk_bf16_f32 v195, v172, v176
	v_cvt_pk_bf16_f32 v196, v177, v180
	v_cvt_pk_bf16_f32 v197, v181, v183
	v_cvt_pk_bf16_f32 v198, v184, v185
	v_cvt_pk_bf16_f32 v199, v186, v188
	v_cvt_pk_bf16_f32 v200, v187, v189
	v_cvt_pk_bf16_f32 v201, v190, v191
	v_cvt_pk_bf16_f32 v202, v121, v122
	v_cvt_pk_bf16_f32 v203, v123, v124
	v_cvt_pk_bf16_f32 v204, v125, v126
	v_cvt_pk_bf16_f32 v205, v127, v129
	v_cvt_pk_bf16_f32 v206, v142, v175
	v_cvt_pk_bf16_f32 v207, v173, v178
	v_cvt_pk_bf16_f32 v208, v179, v182
	v_cvt_pk_bf16_f32 v209, v192, v193
	s_cmp_lg_u32 s73, -5
	s_cselect_b64 s[8:9], -1, 0
	s_cmp_eq_u32 s73, -5
	s_cselect_b64 s[14:15], -1, 0
	s_and_b64 vcc, exec, s[8:9]
	s_cbranch_vccz .Ldf_mask_2

.LBB0_262:
	s_waitcnt lgkmcnt(10)
	v_mfma_f32_32x32x16_bf16 v[2:17], v[210:213], v[194:197], v[2:17]
	ds_read_b64_tr_b16 v[210:211], v150 offset:20480
	ds_read_b64_tr_b16 v[212:213], v151 offset:20480
	v_exp_f32_e32 v121, v66
	v_exp_f32_e32 v122, v67
	s_waitcnt lgkmcnt(10)
	v_mfma_f32_32x32x16_bf16 v[18:33], v[214:217], v[194:197], v[18:33]
	ds_read_b64_tr_b16 v[214:215], v152 offset:20480
	ds_read_b64_tr_b16 v[216:217], v153 offset:20480
	v_exp_f32_e32 v123, v68
	v_exp_f32_e32 v124, v69
	s_waitcnt lgkmcnt(10)
	v_mfma_f32_32x32x16_bf16 v[34:49], v[218:221], v[194:197], v[34:49]
	ds_read_b64_tr_b16 v[218:219], v146 offset:24576
	ds_read_b64_tr_b16 v[220:221], v147 offset:24576
	v_exp_f32_e32 v125, v70
	v_exp_f32_e32 v126, v71
	s_waitcnt lgkmcnt(10)
	v_mfma_f32_32x32x16_bf16 v[50:65], v[222:225], v[194:197], v[50:65]
	ds_read_b64_tr_b16 v[222:223], v148 offset:24576
	ds_read_b64_tr_b16 v[224:225], v149 offset:24576
	v_exp_f32_e32 v127, v72
	v_exp_f32_e32 v129, v73
	v_mov_b32_e32 v238, 0x18020
	ds_read_b128 v[66:69], v238
	v_mov_b32_e32 v239, 0x18030
	ds_read_b128 v[70:73], v239
	s_waitcnt lgkmcnt(12)
	v_mfma_f32_32x32x16_bf16 v[2:17], v[226:229], v[198:201], v[2:17]
	ds_read_b64_tr_b16 v[226:227], v150 offset:24576
	ds_read_b64_tr_b16 v[228:229], v151 offset:24576
	v_exp_f32_e32 v128, v82
	v_exp_f32_e32 v174, v83
	s_waitcnt lgkmcnt(12)
	v_mfma_f32_32x32x16_bf16 v[18:33], v[234:237], v[198:201], v[18:33]
	ds_read_b64_tr_b16 v[234:235], v152 offset:24576
	ds_read_b64_tr_b16 v[236:237], v153 offset:24576
	v_exp_f32_e32 v172, v84
	v_exp_f32_e32 v176, v85
	s_waitcnt lgkmcnt(12)
	v_mfma_f32_32x32x16_bf16 v[34:49], v[210:213], v[198:201], v[34:49]
	ds_read_b64_tr_b16 v[210:211], v146 offset:28672
	ds_read_b64_tr_b16 v[212:213], v147 offset:28672
	v_exp_f32_e32 v177, v86
	v_exp_f32_e32 v180, v87
	s_waitcnt lgkmcnt(12)
	v_mfma_f32_32x32x16_bf16 v[50:65], v[214:217], v[198:201], v[50:65]
	ds_read_b64_tr_b16 v[214:215], v148 offset:28672
	ds_read_b64_tr_b16 v[216:217], v149 offset:28672
	v_exp_f32_e32 v181, v88
	v_exp_f32_e32 v183, v89
	s_waitcnt lgkmcnt(12)
	v_mfma_f32_32x32x16_bf16 v[2:17], v[218:221], v[202:205], v[2:17]
	ds_read_b64_tr_b16 v[218:219], v150 offset:28672
	ds_read_b64_tr_b16 v[220:221], v151 offset:28672
	v_exp_f32_e32 v184, v90
	v_exp_f32_e32 v185, v91
	s_waitcnt lgkmcnt(12)
	v_mfma_f32_32x32x16_bf16 v[18:33], v[222:225], v[202:205], v[18:33]
	ds_read_b64_tr_b16 v[222:223], v152 offset:28672
	ds_read_b64_tr_b16 v[224:225], v153 offset:28672
	v_exp_f32_e32 v186, v92
	v_exp_f32_e32 v188, v93
	s_waitcnt lgkmcnt(10)
	v_mfma_f32_32x32x16_bf16 v[34:49], v[226:229], v[202:205], v[34:49]
	v_exp_f32_e32 v187, v94
	v_exp_f32_e32 v189, v95
	s_waitcnt lgkmcnt(8)
	v_mfma_f32_32x32x16_bf16 v[50:65], v[234:237], v[202:205], v[50:65]
	v_exp_f32_e32 v190, v96
	v_exp_f32_e32 v191, v97
	s_waitcnt lgkmcnt(6)
	v_mfma_f32_32x32x16_bf16 v[2:17], v[210:213], v[206:209], v[2:17]
	v_exp_f32_e32 v142, v74
	v_exp_f32_e32 v175, v75
	v_and_b32_e32 v66, v66, v67
	v_and_b32_e32 v68, v68, v69
	s_waitcnt lgkmcnt(4)
	v_mfma_f32_32x32x16_bf16 v[18:33], v[214:217], v[206:209], v[18:33]
	v_exp_f32_e32 v173, v76
	v_exp_f32_e32 v178, v77
	v_and_b32_e32 v70, v70, v71
	v_and_b32_e32 v72, v72, v73
	s_waitcnt lgkmcnt(2)
	v_mfma_f32_32x32x16_bf16 v[34:49], v[218:221], v[206:209], v[34:49]
	v_exp_f32_e32 v179, v78
	v_exp_f32_e32 v182, v79
	v_and_b32_e32 v66, v66, v68
	v_and_b32_e32 v70, v70, v72
	s_waitcnt lgkmcnt(0)
	v_mfma_f32_32x32x16_bf16 v[50:65], v[222:225], v[206:209], v[50:65]
	v_exp_f32_e32 v192, v80
	v_exp_f32_e32 v193, v81
	v_and_b32_e32 v66, v66, v70
	s_andn2_b64 vcc, exec, s[14:15]
	s_cbranch_vccz .LBB0_269
	s_cmp_gt_i32 s3, s82
	v_mov_b32_e32 v238, 0
	s_cbranch_scc1 .LBB0_264
.LBB0_270:
	s_add_i32 s3, s99, 0
	v_cvt_f32_i32_e32 v238, s3
	v_fma_f32 v238, v145, v238, v119
	v_sub_f32_e32 v238, v238, v120
	v_cmp_gt_f32_e32 vcc, s85, v238
	s_cmp_eq_u64 vcc, exec
	s_cselect_b64 s[8:9], -1, 0
	v_cndmask_b32_e64 v238, 0, 1, s[8:9]
.LBB0_264:
	s_and_saveexec_b64 s[8:9], s[6:7]

.LBB0_269:
	s_nop 3
	v_pk_mul_f32 v[16:17], v[0:1], v[16:17] op_sel_hi:[0,1]
	v_pk_mul_f32 v[14:15], v[0:1], v[14:15] op_sel_hi:[0,1]
	v_pk_mul_f32 v[12:13], v[0:1], v[12:13] op_sel_hi:[0,1]
	v_pk_mul_f32 v[10:11], v[0:1], v[10:11] op_sel_hi:[0,1]
	v_pk_mul_f32 v[8:9], v[0:1], v[8:9] op_sel_hi:[0,1]
	v_pk_mul_f32 v[6:7], v[0:1], v[6:7] op_sel_hi:[0,1]
	v_pk_mul_f32 v[4:5], v[0:1], v[4:5] op_sel_hi:[0,1]
	v_pk_mul_f32 v[2:3], v[0:1], v[2:3] op_sel_hi:[0,1]
	v_pk_mul_f32 v[32:33], v[0:1], v[32:33] op_sel_hi:[0,1]
	v_pk_mul_f32 v[30:31], v[0:1], v[30:31] op_sel_hi:[0,1]
	v_pk_mul_f32 v[28:29], v[0:1], v[28:29] op_sel_hi:[0,1]
	v_pk_mul_f32 v[26:27], v[0:1], v[26:27] op_sel_hi:[0,1]
	v_pk_mul_f32 v[24:25], v[0:1], v[24:25] op_sel_hi:[0,1]
	v_pk_mul_f32 v[22:23], v[0:1], v[22:23] op_sel_hi:[0,1]
	v_pk_mul_f32 v[20:21], v[0:1], v[20:21] op_sel_hi:[0,1]
	v_pk_mul_f32 v[18:19], v[0:1], v[18:19] op_sel_hi:[0,1]
	v_pk_mul_f32 v[48:49], v[0:1], v[48:49] op_sel_hi:[0,1]
	v_pk_mul_f32 v[46:47], v[0:1], v[46:47] op_sel_hi:[0,1]
	v_pk_mul_f32 v[44:45], v[0:1], v[44:45] op_sel_hi:[0,1]
	v_pk_mul_f32 v[42:43], v[0:1], v[42:43] op_sel_hi:[0,1]
	v_pk_mul_f32 v[40:41], v[0:1], v[40:41] op_sel_hi:[0,1]
	v_pk_mul_f32 v[38:39], v[0:1], v[38:39] op_sel_hi:[0,1]
	v_pk_mul_f32 v[36:37], v[0:1], v[36:37] op_sel_hi:[0,1]
	v_pk_mul_f32 v[34:35], v[0:1], v[34:35] op_sel_hi:[0,1]
	v_pk_mul_f32 v[64:65], v[0:1], v[64:65] op_sel_hi:[0,1]
	v_pk_mul_f32 v[62:63], v[0:1], v[62:63] op_sel_hi:[0,1]
	v_pk_mul_f32 v[60:61], v[0:1], v[60:61] op_sel_hi:[0,1]
	v_pk_mul_f32 v[58:59], v[0:1], v[58:59] op_sel_hi:[0,1]
	v_pk_mul_f32 v[56:57], v[0:1], v[56:57] op_sel_hi:[0,1]
	v_pk_mul_f32 v[54:55], v[0:1], v[54:55] op_sel_hi:[0,1]
	v_pk_mul_f32 v[52:53], v[0:1], v[52:53] op_sel_hi:[0,1]
	v_pk_mul_f32 v[50:51], v[0:1], v[50:51] op_sel_hi:[0,1]
	s_cmp_gt_i32 s3, s82
	v_mov_b32_e32 v238, 0
	s_cbranch_scc1 .LBB0_264
	s_branch .LBB0_270
.LBB0_271:
	v_add_f32_e32 v230, v128, v172
	v_add_f32_e32 v231, v174, v176
	v_add_f32_e32 v230, v177, v230
	v_add_f32_e32 v231, v180, v231
	s_waitcnt lgkmcnt(7)
	v_mfma_f32_32x32x16_bf16 v[82:97], v[66:69], v[98:101], 0
	v_add_f32_e32 v230, v181, v230
	v_add_f32_e32 v231, v183, v231
	v_add_f32_e32 v230, v184, v230
	v_add_f32_e32 v231, v185, v231
	s_waitcnt lgkmcnt(6)
	v_mfma_f32_32x32x16_bf16 v[66:81], v[70:73], v[98:101], 0
	v_add_f32_e32 v230, v186, v230
	v_add_f32_e32 v231, v188, v231
	v_add_f32_e32 v230, v187, v230
	v_add_f32_e32 v231, v189, v231
	s_add_i32 s2, s28, 1
	s_max_i32 s96, s2, 0
	s_lshl_b64 s[2:3], s[96:97], 19
	s_add_u32 s2, s74, s2
	s_addc_u32 s3, s75, s3
	s_mov_b32 s8, m0
	s_mov_b32 m0, s53
	s_nop 0
	global_load_lds_dwordx4 v156, s[2:3]
	s_mov_b32 m0, s8
	s_add_u32 s2, s89, s12
	s_addc_u32 s3, s90, s13
	s_mov_b32 s8, m0
	s_mov_b32 m0, s52
	s_nop 0
	global_load_lds_dwordx4 v154, s[2:3]
	s_mov_b32 m0, s8
	s_nop 0
	s_mov_b32 s8, m0
	s_mov_b32 m0, s77
	s_nop 0
	global_load_lds_dwordx4 v155, s[2:3]
	s_mov_b32 m0, s8
	s_waitcnt lgkmcnt(5)
	v_mfma_f32_32x32x16_bf16 v[82:97], v[210:213], v[102:105], v[82:97]
	v_add_f32_e32 v230, v190, v230
	v_add_f32_e32 v231, v191, v231
	v_add_f32_e32 v230, v121, v230
	v_add_f32_e32 v231, v122, v231
	s_waitcnt lgkmcnt(4)
	v_mfma_f32_32x32x16_bf16 v[66:81], v[214:217], v[102:105], v[66:81]
	v_add_f32_e32 v230, v123, v230
	v_add_f32_e32 v231, v124, v231
	v_add_f32_e32 v230, v125, v230
	v_add_f32_e32 v231, v126, v231
	s_waitcnt lgkmcnt(3)
	v_mfma_f32_32x32x16_bf16 v[82:97], v[218:221], v[106:109], v[82:97]
	v_add_f32_e32 v230, v127, v230
	v_add_f32_e32 v231, v129, v231
	v_add_f32_e32 v230, v142, v230
	v_add_f32_e32 v231, v175, v231
	s_waitcnt lgkmcnt(2)
	v_mfma_f32_32x32x16_bf16 v[66:81], v[222:225], v[106:109], v[66:81]
	v_add_f32_e32 v230, v173, v230
	v_add_f32_e32 v231, v178, v231
	v_add_f32_e32 v230, v179, v230
	v_add_f32_e32 v231, v182, v231
	s_waitcnt lgkmcnt(1)
	v_mfma_f32_32x32x16_bf16 v[82:97], v[226:229], v[110:113], v[82:97]
	v_add_f32_e32 v230, v192, v230
	v_add_f32_e32 v231, v193, v231
	v_add_f32_e32 v230, v230, v231
	v_add_f32_e32 v118, v118, v230
	s_waitcnt lgkmcnt(0)
	v_mfma_f32_32x32x16_bf16 v[66:81], v[234:237], v[110:113], v[66:81]
	v_cvt_f32_i32_e32 v238, s79
	v_or_b32_sdwa v132, v238, v157 dst_sel:DWORD dst_unused:UNUSED_PAD src0_sel:WORD_1 src1_sel:DWORD
	v_or_b32_sdwa v133, v238, v157 dst_sel:DWORD dst_unused:UNUSED_PAD src0_sel:WORD_1 src1_sel:DWORD
	ds_read_b64_tr_b16 v[210:211], v146 offset:32768
	ds_read_b64_tr_b16 v[212:213], v147 offset:32768
	ds_read_b64_tr_b16 v[214:215], v148 offset:32768
	ds_read_b64_tr_b16 v[216:217], v149 offset:32768
	v_mfma_f32_32x32x16_bf16 v[82:97], v[132:135], v[114:117], v[82:97]
	v_or_b32_sdwa v132, v238, v158 dst_sel:DWORD dst_unused:UNUSED_PAD src0_sel:WORD_1 src1_sel:DWORD
	v_or_b32_sdwa v133, v238, v158 dst_sel:DWORD dst_unused:UNUSED_PAD src0_sel:WORD_1 src1_sel:DWORD
	ds_read_b64_tr_b16 v[218:219], v150 offset:32768
	ds_read_b64_tr_b16 v[220:221], v151 offset:32768
	ds_read_b64_tr_b16 v[222:223], v152 offset:32768
	ds_read_b64_tr_b16 v[224:225], v153 offset:32768
	v_mfma_f32_32x32x16_bf16 v[66:81], v[132:135], v[114:117], v[66:81]
	ds_read_b64_tr_b16 v[226:227], v146 offset:36864
	ds_read_b64_tr_b16 v[228:229], v147 offset:36864
	ds_read_b64_tr_b16 v[234:235], v148 offset:36864
	ds_read_b64_tr_b16 v[236:237], v149 offset:36864
	v_cvt_pk_bf16_f32 v194, v128, v174
	v_cvt_pk_bf16_f32 v195, v172, v176
	v_cvt_pk_bf16_f32 v196, v177, v180
	v_cvt_pk_bf16_f32 v197, v181, v183
	v_cvt_pk_bf16_f32 v198, v184, v185
	v_cvt_pk_bf16_f32 v199, v186, v188
	v_cvt_pk_bf16_f32 v200, v187, v189
	v_cvt_pk_bf16_f32 v201, v190, v191
	v_cvt_pk_bf16_f32 v202, v121, v122
	v_cvt_pk_bf16_f32 v203, v123, v124
	v_cvt_pk_bf16_f32 v204, v125, v126
	v_cvt_pk_bf16_f32 v205, v127, v129
	v_cvt_pk_bf16_f32 v206, v142, v175
	v_cvt_pk_bf16_f32 v207, v173, v178
	v_cvt_pk_bf16_f32 v208, v179, v182
	v_cvt_pk_bf16_f32 v209, v192, v193
	s_cmp_lg_u32 s73, -4
	s_cselect_b64 s[8:9], -1, 0
	s_cmp_eq_u32 s73, -4
	s_cselect_b64 s[12:13], -1, 0
	s_and_b64 vcc, exec, s[8:9]
	s_cbranch_vccz .Ldf_mask_3

.LBB0_279:
	s_waitcnt lgkmcnt(10)
	v_mfma_f32_32x32x16_bf16 v[2:17], v[210:213], v[194:197], v[2:17]
	ds_read_b64_tr_b16 v[210:211], v150 offset:36864
	ds_read_b64_tr_b16 v[212:213], v151 offset:36864
	v_exp_f32_e32 v121, v66
	v_exp_f32_e32 v122, v67
	s_waitcnt lgkmcnt(10)
	v_mfma_f32_32x32x16_bf16 v[18:33], v[214:217], v[194:197], v[18:33]
	ds_read_b64_tr_b16 v[214:215], v152 offset:36864
	ds_read_b64_tr_b16 v[216:217], v153 offset:36864
	v_exp_f32_e32 v123, v68
	v_exp_f32_e32 v124, v69
	s_waitcnt lgkmcnt(10)
	v_mfma_f32_32x32x16_bf16 v[34:49], v[218:221], v[194:197], v[34:49]
	ds_read_b64_tr_b16 v[218:219], v146 offset:40960
	ds_read_b64_tr_b16 v[220:221], v147 offset:40960
	v_exp_f32_e32 v125, v70
	v_exp_f32_e32 v126, v71
	s_waitcnt lgkmcnt(10)
	v_mfma_f32_32x32x16_bf16 v[50:65], v[222:225], v[194:197], v[50:65]
	ds_read_b64_tr_b16 v[222:223], v148 offset:40960
	ds_read_b64_tr_b16 v[224:225], v149 offset:40960
	v_exp_f32_e32 v127, v72
	v_exp_f32_e32 v129, v73
	v_mov_b32_e32 v238, 0x18000
	ds_read_b128 v[66:69], v238
	v_mov_b32_e32 v239, 0x18010
	ds_read_b128 v[70:73], v239
	s_waitcnt lgkmcnt(12)
	v_mfma_f32_32x32x16_bf16 v[2:17], v[226:229], v[198:201], v[2:17]
	ds_read_b64_tr_b16 v[226:227], v150 offset:40960
	ds_read_b64_tr_b16 v[228:229], v151 offset:40960
	v_exp_f32_e32 v128, v82
	v_exp_f32_e32 v174, v83
	s_waitcnt lgkmcnt(12)
	v_mfma_f32_32x32x16_bf16 v[18:33], v[234:237], v[198:201], v[18:33]
	ds_read_b64_tr_b16 v[234:235], v152 offset:40960
	ds_read_b64_tr_b16 v[236:237], v153 offset:40960
	v_exp_f32_e32 v172, v84
	v_exp_f32_e32 v176, v85
	s_waitcnt lgkmcnt(12)
	v_mfma_f32_32x32x16_bf16 v[34:49], v[210:213], v[198:201], v[34:49]
	ds_read_b64_tr_b16 v[210:211], v146 offset:45056
	ds_read_b64_tr_b16 v[212:213], v147 offset:45056
	v_exp_f32_e32 v177, v86
	v_exp_f32_e32 v180, v87
	s_waitcnt lgkmcnt(12)
	v_mfma_f32_32x32x16_bf16 v[50:65], v[214:217], v[198:201], v[50:65]
	ds_read_b64_tr_b16 v[214:215], v148 offset:45056
	ds_read_b64_tr_b16 v[216:217], v149 offset:45056
	v_exp_f32_e32 v181, v88
	v_exp_f32_e32 v183, v89
	s_waitcnt lgkmcnt(12)
	v_mfma_f32_32x32x16_bf16 v[2:17], v[218:221], v[202:205], v[2:17]
	ds_read_b64_tr_b16 v[218:219], v150 offset:45056
	ds_read_b64_tr_b16 v[220:221], v151 offset:45056
	v_exp_f32_e32 v184, v90
	v_exp_f32_e32 v185, v91
	s_waitcnt lgkmcnt(12)
	v_mfma_f32_32x32x16_bf16 v[18:33], v[222:225], v[202:205], v[18:33]
	ds_read_b64_tr_b16 v[222:223], v152 offset:45056
	ds_read_b64_tr_b16 v[224:225], v153 offset:45056
	v_exp_f32_e32 v186, v92
	v_exp_f32_e32 v188, v93
	s_waitcnt lgkmcnt(10)
	v_mfma_f32_32x32x16_bf16 v[34:49], v[226:229], v[202:205], v[34:49]
	v_exp_f32_e32 v187, v94
	v_exp_f32_e32 v189, v95
	s_waitcnt lgkmcnt(8)
	v_mfma_f32_32x32x16_bf16 v[50:65], v[234:237], v[202:205], v[50:65]
	v_exp_f32_e32 v190, v96
	v_exp_f32_e32 v191, v97
	s_waitcnt lgkmcnt(6)
	v_mfma_f32_32x32x16_bf16 v[2:17], v[210:213], v[206:209], v[2:17]
	v_exp_f32_e32 v142, v74
	v_exp_f32_e32 v175, v75
	v_and_b32_e32 v66, v66, v67
	v_and_b32_e32 v68, v68, v69
	s_waitcnt lgkmcnt(4)
	v_mfma_f32_32x32x16_bf16 v[18:33], v[214:217], v[206:209], v[18:33]
	v_exp_f32_e32 v173, v76
	v_exp_f32_e32 v178, v77
	v_and_b32_e32 v70, v70, v71
	v_and_b32_e32 v72, v72, v73
	s_waitcnt lgkmcnt(2)
	v_mfma_f32_32x32x16_bf16 v[34:49], v[218:221], v[206:209], v[34:49]
	v_exp_f32_e32 v179, v78
	v_exp_f32_e32 v182, v79
	v_and_b32_e32 v66, v66, v68
	v_and_b32_e32 v70, v70, v72
	s_waitcnt lgkmcnt(0)
	v_mfma_f32_32x32x16_bf16 v[50:65], v[222:225], v[206:209], v[50:65]
	v_exp_f32_e32 v192, v80
	v_exp_f32_e32 v193, v81
	v_and_b32_e32 v66, v66, v70
	s_andn2_b64 vcc, exec, s[12:13]
	s_cbranch_vccz .LBB0_284
	s_add_i32 s28, s28, 4
	s_cmp_gt_i32 s28, s82
	v_mov_b32_e32 v238, 0
	s_cbranch_scc1 .LBB0_281
.LBB0_285:
	s_add_i32 s2, s99, 0xffffffc0
	v_cvt_f32_i32_e32 v238, s2
	v_fma_f32 v238, v145, v238, v119
	v_sub_f32_e32 v238, v238, v120
	v_cmp_gt_f32_e32 vcc, s85, v238
	s_cmp_eq_u64 vcc, exec
	s_cselect_b64 s[2:3], -1, 0
	v_cndmask_b32_e64 v238, 0, 1, s[2:3]
.LBB0_281:
	s_and_saveexec_b64 s[8:9], s[6:7]

.LBB0_284:
	s_nop 3
	v_pk_mul_f32 v[16:17], v[0:1], v[16:17] op_sel_hi:[0,1]
	v_pk_mul_f32 v[14:15], v[0:1], v[14:15] op_sel_hi:[0,1]
	v_pk_mul_f32 v[12:13], v[0:1], v[12:13] op_sel_hi:[0,1]
	v_pk_mul_f32 v[10:11], v[0:1], v[10:11] op_sel_hi:[0,1]
	v_pk_mul_f32 v[8:9], v[0:1], v[8:9] op_sel_hi:[0,1]
	v_pk_mul_f32 v[6:7], v[0:1], v[6:7] op_sel_hi:[0,1]
	v_pk_mul_f32 v[4:5], v[0:1], v[4:5] op_sel_hi:[0,1]
	v_pk_mul_f32 v[2:3], v[0:1], v[2:3] op_sel_hi:[0,1]
	v_pk_mul_f32 v[32:33], v[0:1], v[32:33] op_sel_hi:[0,1]
	v_pk_mul_f32 v[30:31], v[0:1], v[30:31] op_sel_hi:[0,1]
	v_pk_mul_f32 v[28:29], v[0:1], v[28:29] op_sel_hi:[0,1]
	v_pk_mul_f32 v[26:27], v[0:1], v[26:27] op_sel_hi:[0,1]
	v_pk_mul_f32 v[24:25], v[0:1], v[24:25] op_sel_hi:[0,1]
	v_pk_mul_f32 v[22:23], v[0:1], v[22:23] op_sel_hi:[0,1]
	v_pk_mul_f32 v[20:21], v[0:1], v[20:21] op_sel_hi:[0,1]
	v_pk_mul_f32 v[18:19], v[0:1], v[18:19] op_sel_hi:[0,1]
	v_pk_mul_f32 v[48:49], v[0:1], v[48:49] op_sel_hi:[0,1]
	v_pk_mul_f32 v[46:47], v[0:1], v[46:47] op_sel_hi:[0,1]
	v_pk_mul_f32 v[44:45], v[0:1], v[44:45] op_sel_hi:[0,1]
	v_pk_mul_f32 v[42:43], v[0:1], v[42:43] op_sel_hi:[0,1]
	v_pk_mul_f32 v[40:41], v[0:1], v[40:41] op_sel_hi:[0,1]
	v_pk_mul_f32 v[38:39], v[0:1], v[38:39] op_sel_hi:[0,1]
	v_pk_mul_f32 v[36:37], v[0:1], v[36:37] op_sel_hi:[0,1]
	v_pk_mul_f32 v[34:35], v[0:1], v[34:35] op_sel_hi:[0,1]
	v_pk_mul_f32 v[64:65], v[0:1], v[64:65] op_sel_hi:[0,1]
	v_pk_mul_f32 v[62:63], v[0:1], v[62:63] op_sel_hi:[0,1]
	v_pk_mul_f32 v[60:61], v[0:1], v[60:61] op_sel_hi:[0,1]
	v_pk_mul_f32 v[58:59], v[0:1], v[58:59] op_sel_hi:[0,1]
	v_pk_mul_f32 v[56:57], v[0:1], v[56:57] op_sel_hi:[0,1]
	v_pk_mul_f32 v[54:55], v[0:1], v[54:55] op_sel_hi:[0,1]
	v_pk_mul_f32 v[52:53], v[0:1], v[52:53] op_sel_hi:[0,1]
	v_pk_mul_f32 v[50:51], v[0:1], v[50:51] op_sel_hi:[0,1]
	s_add_i32 s28, s28, 4
	s_cmp_gt_i32 s28, s82
	v_mov_b32_e32 v238, 0
	s_cbranch_scc1 .LBB0_281
	s_branch .LBB0_285
.Ldf_mask_0:
	v_sub_f32_e32 v230, 0, v159
	v_sub_f32_e32 v231, 0x3f800000, v159
	v_max_f32_e32 v230, 0, v230
	v_max_f32_e32 v231, 0, v231
	v_pk_fma_f32 v[82:83], s[16:17], v[230:231], v[82:83] neg_lo:[1,0,0] neg_hi:[1,0,0]
	v_sub_f32_e32 v238, 0x40000000, v159
	v_sub_f32_e32 v239, 0x40400000, v159
	v_max_f32_e32 v238, 0, v238
	v_max_f32_e32 v239, 0, v239
	v_pk_fma_f32 v[84:85], s[16:17], v[238:239], v[84:85] neg_lo:[1,0,0] neg_hi:[1,0,0]
	v_sub_f32_e32 v230, 0x40800000, v159
	v_sub_f32_e32 v231, 0x40a00000, v159
	v_max_f32_e32 v230, 0, v230
	v_max_f32_e32 v231, 0, v231
	v_pk_fma_f32 v[86:87], s[16:17], v[230:231], v[86:87] neg_lo:[1,0,0] neg_hi:[1,0,0]
	v_sub_f32_e32 v238, 0x40c00000, v159
	v_sub_f32_e32 v239, 0x40e00000, v159
	v_max_f32_e32 v238, 0, v238
	v_max_f32_e32 v239, 0, v239
	v_pk_fma_f32 v[88:89], s[16:17], v[238:239], v[88:89] neg_lo:[1,0,0] neg_hi:[1,0,0]
	v_sub_f32_e32 v230, 0x41800000, v159
	v_sub_f32_e32 v231, 0x41880000, v159
	v_max_f32_e32 v230, 0, v230
	v_max_f32_e32 v231, 0, v231
	v_pk_fma_f32 v[90:91], s[16:17], v[230:231], v[90:91] neg_lo:[1,0,0] neg_hi:[1,0,0]
	v_sub_f32_e32 v238, 0x41900000, v159
	v_sub_f32_e32 v239, 0x41980000, v159
	v_max_f32_e32 v238, 0, v238
	v_max_f32_e32 v239, 0, v239
	v_pk_fma_f32 v[92:93], s[16:17], v[238:239], v[92:93] neg_lo:[1,0,0] neg_hi:[1,0,0]
	v_sub_f32_e32 v230, 0x41a00000, v159
	v_sub_f32_e32 v231, 0x41a80000, v159
	v_max_f32_e32 v230, 0, v230
	v_max_f32_e32 v231, 0, v231
	v_pk_fma_f32 v[94:95], s[16:17], v[230:231], v[94:95] neg_lo:[1,0,0] neg_hi:[1,0,0]
	v_sub_f32_e32 v238, 0x41b00000, v159
	v_sub_f32_e32 v239, 0x41b80000, v159
	v_max_f32_e32 v238, 0, v238
	v_max_f32_e32 v239, 0, v239
	v_pk_fma_f32 v[96:97], s[16:17], v[238:239], v[96:97] neg_lo:[1,0,0] neg_hi:[1,0,0]
	v_sub_f32_e32 v230, 0x42000000, v159
	v_sub_f32_e32 v231, 0x42040000, v159
	v_max_f32_e32 v230, 0, v230
	v_max_f32_e32 v231, 0, v231
	v_pk_fma_f32 v[66:67], s[16:17], v[230:231], v[66:67] neg_lo:[1,0,0] neg_hi:[1,0,0]
	v_sub_f32_e32 v238, 0x42080000, v159
	v_sub_f32_e32 v239, 0x420c0000, v159
	v_max_f32_e32 v238, 0, v238
	v_max_f32_e32 v239, 0, v239
	v_pk_fma_f32 v[68:69], s[16:17], v[238:239], v[68:69] neg_lo:[1,0,0] neg_hi:[1,0,0]
	v_sub_f32_e32 v230, 0x42100000, v159
	v_sub_f32_e32 v231, 0x42140000, v159
	v_max_f32_e32 v230, 0, v230
	v_max_f32_e32 v231, 0, v231
	v_pk_fma_f32 v[70:71], s[16:17], v[230:231], v[70:71] neg_lo:[1,0,0] neg_hi:[1,0,0]
	v_sub_f32_e32 v238, 0x42180000, v159
	v_sub_f32_e32 v239, 0x421c0000, v159
	v_max_f32_e32 v238, 0, v238
	v_max_f32_e32 v239, 0, v239
	v_pk_fma_f32 v[72:73], s[16:17], v[238:239], v[72:73] neg_lo:[1,0,0] neg_hi:[1,0,0]
	v_sub_f32_e32 v230, 0x42400000, v159
	v_sub_f32_e32 v231, 0x42440000, v159
	v_max_f32_e32 v230, 0, v230
	v_max_f32_e32 v231, 0, v231
	v_pk_fma_f32 v[74:75], s[16:17], v[230:231], v[74:75] neg_lo:[1,0,0] neg_hi:[1,0,0]
	v_sub_f32_e32 v238, 0x42480000, v159
	v_sub_f32_e32 v239, 0x424c0000, v159
	v_max_f32_e32 v238, 0, v238
	v_max_f32_e32 v239, 0, v239
	v_pk_fma_f32 v[76:77], s[16:17], v[238:239], v[76:77] neg_lo:[1,0,0] neg_hi:[1,0,0]
	v_sub_f32_e32 v230, 0x42500000, v159
	v_sub_f32_e32 v231, 0x42540000, v159
	v_max_f32_e32 v230, 0, v230
	v_max_f32_e32 v231, 0, v231
	v_pk_fma_f32 v[78:79], s[16:17], v[230:231], v[78:79] neg_lo:[1,0,0] neg_hi:[1,0,0]
	v_sub_f32_e32 v238, 0x42580000, v159
	v_sub_f32_e32 v239, 0x425c0000, v159
	v_max_f32_e32 v238, 0, v238
	v_max_f32_e32 v239, 0, v239
	v_pk_fma_f32 v[80:81], s[16:17], v[238:239], v[80:81] neg_lo:[1,0,0] neg_hi:[1,0,0]
	s_branch .LBB0_224

.Ldf_resc_0:
	v_max_f32_e32 v0, v132, v132
	v_max_f32_e32 v0, 0, v0
	v_cndmask_b32_e64 v0, v132, v0, s[8:9]
	v_add_f32_e32 v120, v120, v0
	v_xor_b32_e32 v115, 0x80000000, v120
	v_bfe_u32 v116, v115, 16, 1
	v_add3_u32 v115, v115, v116, s98
	v_and_b32_e32 v116, 0xffff0000, v115
	v_sub_f32_e64 v116, -v120, v116
	v_bfe_u32 v117, v116, 16, 1
	v_add3_u32 v117, v116, v117, s98
	v_and_b32_e32 v117, 0xffff0000, v117
	v_exp_f32_e64 v114, -v0
	v_sub_f32_e32 v116, v116, v117
	v_bfe_u32 v132, v116, 16, 1
	v_add3_u32 v116, v116, v132, s98
	v_lshrrev_b32_e32 v116, 16, v116
	v_or_b32_sdwa v115, v117, v115 dst_sel:DWORD dst_unused:UNUSED_PAD src0_sel:DWORD src1_sel:WORD_1
	v_cndmask_b32_e64 v132, 0, v115, s[4:5]
	v_cndmask_b32_e64 v133, 0, v116, s[4:5]
	v_pk_add_f32 v[82:83], v[82:83], v[0:1] op_sel_hi:[1,0] neg_lo:[0,1] neg_hi:[0,1]
	v_pk_add_f32 v[66:67], v[66:67], v[0:1] op_sel_hi:[1,0] neg_lo:[0,1] neg_hi:[0,1]
	v_pk_add_f32 v[84:85], v[84:85], v[0:1] op_sel_hi:[1,0] neg_lo:[0,1] neg_hi:[0,1]
	v_pk_add_f32 v[68:69], v[68:69], v[0:1] op_sel_hi:[1,0] neg_lo:[0,1] neg_hi:[0,1]
	v_pk_add_f32 v[86:87], v[86:87], v[0:1] op_sel_hi:[1,0] neg_lo:[0,1] neg_hi:[0,1]
	v_pk_add_f32 v[70:71], v[70:71], v[0:1] op_sel_hi:[1,0] neg_lo:[0,1] neg_hi:[0,1]
	v_pk_add_f32 v[88:89], v[88:89], v[0:1] op_sel_hi:[1,0] neg_lo:[0,1] neg_hi:[0,1]
	v_pk_add_f32 v[72:73], v[72:73], v[0:1] op_sel_hi:[1,0] neg_lo:[0,1] neg_hi:[0,1]
	v_pk_add_f32 v[90:91], v[90:91], v[0:1] op_sel_hi:[1,0] neg_lo:[0,1] neg_hi:[0,1]
	v_pk_add_f32 v[74:75], v[74:75], v[0:1] op_sel_hi:[1,0] neg_lo:[0,1] neg_hi:[0,1]
	v_pk_add_f32 v[92:93], v[92:93], v[0:1] op_sel_hi:[1,0] neg_lo:[0,1] neg_hi:[0,1]
	v_pk_add_f32 v[76:77], v[76:77], v[0:1] op_sel_hi:[1,0] neg_lo:[0,1] neg_hi:[0,1]
	v_pk_add_f32 v[94:95], v[94:95], v[0:1] op_sel_hi:[1,0] neg_lo:[0,1] neg_hi:[0,1]
	v_pk_add_f32 v[78:79], v[78:79], v[0:1] op_sel_hi:[1,0] neg_lo:[0,1] neg_hi:[0,1]
	v_pk_add_f32 v[96:97], v[96:97], v[0:1] op_sel_hi:[1,0] neg_lo:[0,1] neg_hi:[0,1]
	v_pk_add_f32 v[80:81], v[80:81], v[0:1] op_sel_hi:[1,0] neg_lo:[0,1] neg_hi:[0,1]
	v_cndmask_b32_e64 v0, 1.0, v114, s[8:9]
	v_mov_b64_e32 v[114:115], v[130:131]
	v_mul_f32_e32 v118, v118, v0
	s_mov_b64 s[12:13], s[8:9]
	v_mov_b64_e32 v[116:117], v[132:133]
	s_branch .LBB0_231

.Ldf_resc_1:
	v_max_f32_e32 v0, v132, v132
	v_max_f32_e32 v0, 0, v0
	v_cndmask_b32_e64 v0, v132, v0, s[12:13]
	v_add_f32_e32 v120, v120, v0
	v_xor_b32_e32 v115, 0x80000000, v120
	v_bfe_u32 v116, v115, 16, 1
	v_add3_u32 v115, v115, v116, s98
	v_and_b32_e32 v116, 0xffff0000, v115
	v_sub_f32_e64 v116, -v120, v116
	v_bfe_u32 v117, v116, 16, 1
	v_add3_u32 v117, v116, v117, s98
	v_and_b32_e32 v117, 0xffff0000, v117
	v_exp_f32_e64 v114, -v0
	v_sub_f32_e32 v116, v116, v117
	v_bfe_u32 v132, v116, 16, 1
	v_add3_u32 v116, v116, v132, s98
	v_lshrrev_b32_e32 v116, 16, v116
	v_or_b32_sdwa v115, v117, v115 dst_sel:DWORD dst_unused:UNUSED_PAD src0_sel:DWORD src1_sel:WORD_1
	v_cndmask_b32_e64 v132, 0, v115, s[4:5]
	v_cndmask_b32_e64 v133, 0, v116, s[4:5]
	v_pk_add_f32 v[82:83], v[82:83], v[0:1] op_sel_hi:[1,0] neg_lo:[0,1] neg_hi:[0,1]
	v_pk_add_f32 v[66:67], v[66:67], v[0:1] op_sel_hi:[1,0] neg_lo:[0,1] neg_hi:[0,1]
	v_pk_add_f32 v[84:85], v[84:85], v[0:1] op_sel_hi:[1,0] neg_lo:[0,1] neg_hi:[0,1]
	v_pk_add_f32 v[68:69], v[68:69], v[0:1] op_sel_hi:[1,0] neg_lo:[0,1] neg_hi:[0,1]
	v_pk_add_f32 v[86:87], v[86:87], v[0:1] op_sel_hi:[1,0] neg_lo:[0,1] neg_hi:[0,1]
	v_pk_add_f32 v[70:71], v[70:71], v[0:1] op_sel_hi:[1,0] neg_lo:[0,1] neg_hi:[0,1]
	v_pk_add_f32 v[88:89], v[88:89], v[0:1] op_sel_hi:[1,0] neg_lo:[0,1] neg_hi:[0,1]
	v_pk_add_f32 v[72:73], v[72:73], v[0:1] op_sel_hi:[1,0] neg_lo:[0,1] neg_hi:[0,1]
	v_pk_add_f32 v[90:91], v[90:91], v[0:1] op_sel_hi:[1,0] neg_lo:[0,1] neg_hi:[0,1]
	v_pk_add_f32 v[74:75], v[74:75], v[0:1] op_sel_hi:[1,0] neg_lo:[0,1] neg_hi:[0,1]
	v_pk_add_f32 v[92:93], v[92:93], v[0:1] op_sel_hi:[1,0] neg_lo:[0,1] neg_hi:[0,1]
	v_pk_add_f32 v[76:77], v[76:77], v[0:1] op_sel_hi:[1,0] neg_lo:[0,1] neg_hi:[0,1]
	v_pk_add_f32 v[94:95], v[94:95], v[0:1] op_sel_hi:[1,0] neg_lo:[0,1] neg_hi:[0,1]
	v_pk_add_f32 v[78:79], v[78:79], v[0:1] op_sel_hi:[1,0] neg_lo:[0,1] neg_hi:[0,1]
	v_pk_add_f32 v[96:97], v[96:97], v[0:1] op_sel_hi:[1,0] neg_lo:[0,1] neg_hi:[0,1]
	v_pk_add_f32 v[80:81], v[80:81], v[0:1] op_sel_hi:[1,0] neg_lo:[0,1] neg_hi:[0,1]
	v_cndmask_b32_e64 v0, 1.0, v114, s[12:13]
	v_mov_b64_e32 v[114:115], v[130:131]
	v_mul_f32_e32 v118, v118, v0
	s_mov_b64 s[14:15], s[12:13]
	v_mov_b64_e32 v[116:117], v[132:133]
	s_branch .LBB0_246
.LBB0_240:
	s_nop 3
	v_pk_mul_f32 v[16:17], v[0:1], v[16:17] op_sel_hi:[0,1]
	v_pk_mul_f32 v[14:15], v[0:1], v[14:15] op_sel_hi:[0,1]
	v_pk_mul_f32 v[12:13], v[0:1], v[12:13] op_sel_hi:[0,1]
	v_pk_mul_f32 v[10:11], v[0:1], v[10:11] op_sel_hi:[0,1]
	v_pk_mul_f32 v[8:9], v[0:1], v[8:9] op_sel_hi:[0,1]
	v_pk_mul_f32 v[6:7], v[0:1], v[6:7] op_sel_hi:[0,1]
	v_pk_mul_f32 v[4:5], v[0:1], v[4:5] op_sel_hi:[0,1]
	v_pk_mul_f32 v[2:3], v[0:1], v[2:3] op_sel_hi:[0,1]
	v_pk_mul_f32 v[32:33], v[0:1], v[32:33] op_sel_hi:[0,1]
	v_pk_mul_f32 v[30:31], v[0:1], v[30:31] op_sel_hi:[0,1]
	v_pk_mul_f32 v[28:29], v[0:1], v[28:29] op_sel_hi:[0,1]
	v_pk_mul_f32 v[26:27], v[0:1], v[26:27] op_sel_hi:[0,1]
	v_pk_mul_f32 v[24:25], v[0:1], v[24:25] op_sel_hi:[0,1]
	v_pk_mul_f32 v[22:23], v[0:1], v[22:23] op_sel_hi:[0,1]
	v_pk_mul_f32 v[20:21], v[0:1], v[20:21] op_sel_hi:[0,1]
	v_pk_mul_f32 v[18:19], v[0:1], v[18:19] op_sel_hi:[0,1]
	v_pk_mul_f32 v[48:49], v[0:1], v[48:49] op_sel_hi:[0,1]
	v_pk_mul_f32 v[46:47], v[0:1], v[46:47] op_sel_hi:[0,1]
	v_pk_mul_f32 v[44:45], v[0:1], v[44:45] op_sel_hi:[0,1]
	v_pk_mul_f32 v[42:43], v[0:1], v[42:43] op_sel_hi:[0,1]
	v_pk_mul_f32 v[40:41], v[0:1], v[40:41] op_sel_hi:[0,1]
	v_pk_mul_f32 v[38:39], v[0:1], v[38:39] op_sel_hi:[0,1]
	v_pk_mul_f32 v[36:37], v[0:1], v[36:37] op_sel_hi:[0,1]
	v_pk_mul_f32 v[34:35], v[0:1], v[34:35] op_sel_hi:[0,1]
	v_pk_mul_f32 v[64:65], v[0:1], v[64:65] op_sel_hi:[0,1]
	v_pk_mul_f32 v[62:63], v[0:1], v[62:63] op_sel_hi:[0,1]
	v_pk_mul_f32 v[60:61], v[0:1], v[60:61] op_sel_hi:[0,1]
	v_pk_mul_f32 v[58:59], v[0:1], v[58:59] op_sel_hi:[0,1]
	v_pk_mul_f32 v[56:57], v[0:1], v[56:57] op_sel_hi:[0,1]
	v_pk_mul_f32 v[54:55], v[0:1], v[54:55] op_sel_hi:[0,1]
	v_pk_mul_f32 v[52:53], v[0:1], v[52:53] op_sel_hi:[0,1]
	v_pk_mul_f32 v[50:51], v[0:1], v[50:51] op_sel_hi:[0,1]
	s_add_i32 s2, s28, 7
	s_cmp_gt_i32 s2, s82
	v_mov_b32_e32 v238, 0
	s_cbranch_scc1 .LBB0_233
	s_branch .LBB0_241

.Ldf_resc_2:
	v_max_f32_e32 v0, v132, v132
	v_max_f32_e32 v0, 0, v0
	v_cndmask_b32_e64 v0, v132, v0, s[8:9]
	v_add_f32_e32 v120, v120, v0
	v_xor_b32_e32 v115, 0x80000000, v120
	v_bfe_u32 v116, v115, 16, 1
	v_add3_u32 v115, v115, v116, s98
	v_and_b32_e32 v116, 0xffff0000, v115
	v_sub_f32_e64 v116, -v120, v116
	v_bfe_u32 v117, v116, 16, 1
	v_add3_u32 v117, v116, v117, s98
	v_and_b32_e32 v117, 0xffff0000, v117
	v_exp_f32_e64 v114, -v0
	v_sub_f32_e32 v116, v116, v117
	v_bfe_u32 v132, v116, 16, 1
	v_add3_u32 v116, v116, v132, s98
	v_lshrrev_b32_e32 v116, 16, v116
	v_or_b32_sdwa v115, v117, v115 dst_sel:DWORD dst_unused:UNUSED_PAD src0_sel:DWORD src1_sel:WORD_1
	v_cndmask_b32_e64 v132, 0, v115, s[4:5]
	v_cndmask_b32_e64 v133, 0, v116, s[4:5]
	v_pk_add_f32 v[82:83], v[82:83], v[0:1] op_sel_hi:[1,0] neg_lo:[0,1] neg_hi:[0,1]
	v_pk_add_f32 v[66:67], v[66:67], v[0:1] op_sel_hi:[1,0] neg_lo:[0,1] neg_hi:[0,1]
	v_pk_add_f32 v[84:85], v[84:85], v[0:1] op_sel_hi:[1,0] neg_lo:[0,1] neg_hi:[0,1]
	v_pk_add_f32 v[68:69], v[68:69], v[0:1] op_sel_hi:[1,0] neg_lo:[0,1] neg_hi:[0,1]
	v_pk_add_f32 v[86:87], v[86:87], v[0:1] op_sel_hi:[1,0] neg_lo:[0,1] neg_hi:[0,1]
	v_pk_add_f32 v[70:71], v[70:71], v[0:1] op_sel_hi:[1,0] neg_lo:[0,1] neg_hi:[0,1]
	v_pk_add_f32 v[88:89], v[88:89], v[0:1] op_sel_hi:[1,0] neg_lo:[0,1] neg_hi:[0,1]
	v_pk_add_f32 v[72:73], v[72:73], v[0:1] op_sel_hi:[1,0] neg_lo:[0,1] neg_hi:[0,1]
	v_pk_add_f32 v[90:91], v[90:91], v[0:1] op_sel_hi:[1,0] neg_lo:[0,1] neg_hi:[0,1]
	v_pk_add_f32 v[74:75], v[74:75], v[0:1] op_sel_hi:[1,0] neg_lo:[0,1] neg_hi:[0,1]
	v_pk_add_f32 v[92:93], v[92:93], v[0:1] op_sel_hi:[1,0] neg_lo:[0,1] neg_hi:[0,1]
	v_pk_add_f32 v[76:77], v[76:77], v[0:1] op_sel_hi:[1,0] neg_lo:[0,1] neg_hi:[0,1]
	v_pk_add_f32 v[94:95], v[94:95], v[0:1] op_sel_hi:[1,0] neg_lo:[0,1] neg_hi:[0,1]
	v_pk_add_f32 v[78:79], v[78:79], v[0:1] op_sel_hi:[1,0] neg_lo:[0,1] neg_hi:[0,1]
	v_pk_add_f32 v[96:97], v[96:97], v[0:1] op_sel_hi:[1,0] neg_lo:[0,1] neg_hi:[0,1]
	v_pk_add_f32 v[80:81], v[80:81], v[0:1] op_sel_hi:[1,0] neg_lo:[0,1] neg_hi:[0,1]
	v_cndmask_b32_e64 v0, 1.0, v114, s[8:9]
	v_mov_b64_e32 v[114:115], v[130:131]
	v_mul_f32_e32 v118, v118, v0
	s_mov_b64 s[14:15], s[8:9]
	v_mov_b64_e32 v[116:117], v[132:133]
	s_branch .LBB0_262
